# NORM loop: loop-invariant norm-gain loads hoisted out of the row loop (12 instead of 16 loads per row)
# speedup vs baseline: 1.0001x; 1.0001x over previous
.LBB0_829:
	s_ashr_i32 s3, s3, 6
	s_add_i32 s4, s3, s67
	s_mov_b64 s[10:11], s[54:55]
	s_cmpk_gt_i32 s4, 0x3fff
	s_cbranch_scc1 .LBB0_832
	s_mul_i32 s86, s14, 0x9000
	s_lshl_b64 s[10:11], s[86:87], 2
	s_add_u32 s3, s6, s10
	s_addc_u32 s10, s7, s11
	s_lshl_b32 s11, s15, 1
	s_ashr_i32 s5, s4, 31
	s_add_i32 s11, s11, 6
	s_lshl_b32 s86, s14, 10
	s_lshl_b64 s[14:15], s[4:5], 11
	v_and_b32_e32 v1, 63, v0
	s_add_u32 s6, s6, s14
	v_lshlrev_b32_e32 v204, 3, v1
	s_addc_u32 s7, s7, s15
	v_lshl_add_u64 v[8:9], s[6:7], 0, v[204:205]
	s_mov_b64 s[6:7], 0x8600000
	v_lshl_add_u64 v[20:21], v[8:9], 0, s[6:7]
	s_lshl_b64 s[6:7], s[4:5], 12
	v_lshlrev_b32_e32 v0, 2, v1
	s_add_u32 s6, s8, s6
	v_or_b32_e32 v2, 0x100, v0
	v_or_b32_e32 v4, 0x200, v0
	v_or_b32_e32 v6, 0x300, v0
	v_lshlrev_b32_e32 v204, 4, v1
	s_addc_u32 s7, s9, s7
	v_readlane_b32 s20, v253, 44
	v_readlane_b32 s22, v253, 56
	v_readlane_b32 s24, v253, 58
	v_lshl_add_u64 v[22:23], s[6:7], 0, v[204:205]
	s_lshl_b64 s[6:7], s[86:87], 2
	v_lshlrev_b32_e32 v204, 2, v0
	v_lshlrev_b32_e32 v24, 2, v2
	v_lshlrev_b32_e32 v26, 2, v4
	v_lshlrev_b32_e32 v28, 2, v6
	s_mov_b32 s18, 0xffff0000
	s_mov_b32 s19, 0x800000
	v_readlane_b32 s21, v253, 45
	v_readlane_b32 s23, v253, 57
	v_readlane_b32 s25, v253, 59
	s_nop 3
	s_add_u32 s16, s20, s6
	s_addc_u32 s17, s21, s7
	v_lshl_add_u64 v[156:157], s[16:17], 0, v[204:205]
	global_load_dwordx4 v[132:135], v[156:157], off
	global_load_dwordx4 v[136:139], v[156:157], off offset:1024
	global_load_dwordx4 v[140:143], v[156:157], off offset:2048
	global_load_dwordx4 v[144:147], v[156:157], off offset:3072
.LBB0_831:
	global_load_dwordx4 v[12:15], v[22:23], off
	global_load_dwordx4 v[8:11], v[22:23], off offset:1024
	global_load_dwordx4 v[4:7], v[22:23], off offset:2048
	global_load_dwordx4 v[0:3], v[22:23], off offset:3072
	s_ashr_i32 s5, s4, 13
	s_add_i32 s5, s11, s5
	s_ashr_i32 s14, s4, 11
	s_and_b64 s[8:9], s[0:1], exec
	s_cselect_b32 s5, s14, s5
	s_mul_i32 s8, s5, 0xc00
	s_ashr_i32 s9, s8, 31
	s_lshl_b64 s[8:9], s[8:9], 2
	s_add_u32 s14, s3, s8
	s_addc_u32 s15, s10, s9
	s_add_u32 s8, s14, 0x1000
	s_addc_u32 s9, s15, 0
	v_lshl_add_u64 v[32:33], s[14:15], 0, v[204:205]
	v_lshl_add_u64 v[38:39], s[8:9], 0, v[204:205]
	global_load_dwordx4 v[100:103], v[32:33], off
	global_load_dwordx4 v[116:119], v[38:39], off
	global_load_dwordx4 v[104:107], v[32:33], off offset:1024
	global_load_dwordx4 v[120:123], v[38:39], off offset:1024
	global_load_dwordx4 v[108:111], v[32:33], off offset:2048
	global_load_dwordx4 v[124:127], v[38:39], off offset:2048
	global_load_dwordx4 v[112:115], v[32:33], off offset:3072
	global_load_dwordx4 v[128:131], v[38:39], off offset:3072
	v_lshl_add_u64 v[22:23], v[22:23], 0, s[24:25]
	s_waitcnt vmcnt(8)
	v_pk_mul_f32 v[148:149], v[14:15], v[14:15]
	v_pk_mul_f32 v[150:151], v[12:13], v[12:13]
	s_nop 0
	v_pk_mov_b32 v[152:153], v[150:151], v[148:149] op_sel:[1,0]
	v_mov_b32_e32 v151, v149
	v_pk_add_f32 v[16:17], v[152:153], v[150:151]
	v_pk_mul_f32 v[148:149], v[10:11], v[10:11]
	v_pk_mul_f32 v[150:151], v[8:9], v[8:9]
	v_pk_add_f32 v[16:17], v[16:17], v[16:17] op_sel:[0,1] op_sel_hi:[1,0]
	v_pk_mov_b32 v[152:153], v[150:151], v[148:149] op_sel:[1,0]
	v_mov_b32_e32 v151, v149
	v_pk_add_f32 v[18:19], v[152:153], v[150:151]
	s_nop 0
	v_pk_add_f32 v[18:19], v[18:19], v[18:19] op_sel:[0,1] op_sel_hi:[1,0]
	v_mul_f32_e32 v30, v7, v7
	v_mul_f32_e32 v25, v0, v0
	v_mul_f32_e32 v27, v1, v1
	v_mov_b32_e32 v17, v25
	v_mov_b32_e32 v19, v27
	v_pk_add_f32 v[16:17], v[16:17], v[18:19]
	v_mul_f32_e32 v18, v5, v5
	v_mul_f32_e32 v29, v2, v2
	v_mul_f32_e32 v32, v3, v3
	v_pk_fma_f32 v[18:19], v[4:5], v[4:5], v[18:19] op_sel_hi:[1,1,0]
	v_pk_fma_f32 v[30:31], v[6:7], v[6:7], v[30:31] op_sel_hi:[1,1,0]
	v_mov_b32_e32 v19, v29
	v_mov_b32_e32 v31, v32
	v_pk_add_f32 v[18:19], v[18:19], v[30:31]
	s_nop 0
	v_pk_add_f32 v[16:17], v[16:17], v[18:19]
	s_nop 0
	v_add_f32_e32 v16, v16, v17
	ds_swizzle_b32 v17, v16 offset:swizzle(SWAP,1)
	v_mov_b32_e32 v25, v205
	v_mov_b32_e32 v27, v205
	v_mov_b32_e32 v29, v205
	s_waitcnt lgkmcnt(0)
	v_add_f32_e32 v16, v16, v17
	ds_swizzle_b32 v17, v16 offset:swizzle(SWAP,2)
	s_waitcnt lgkmcnt(0)
	v_add_f32_e32 v16, v16, v17
	ds_swizzle_b32 v17, v16 offset:swizzle(SWAP,4)
	s_waitcnt lgkmcnt(0)
	v_add_f32_e32 v16, v16, v17
	ds_swizzle_b32 v17, v16 offset:swizzle(SWAP,8)
	s_waitcnt lgkmcnt(0)
	v_add_f32_e32 v16, v16, v17
	ds_swizzle_b32 v17, v16 offset:swizzle(SWAP,16)
	s_waitcnt lgkmcnt(0)
	v_add_f32_e32 v16, v16, v17
	v_mov_b32_e32 v17, v220
	v_lshlrev_b32_e32 v17, 2, v17
	v_bitop3_b32 v17, v17, s88, v227 bitop3:0x6c
	ds_bpermute_b32 v17, v17, v16
	s_waitcnt lgkmcnt(0)
	v_add_f32_e32 v16, v16, v17
	v_fmamk_f32 v16, v16, 0x3a800000, v224
	v_cmp_gt_f32_e32 vcc, s19, v16
	v_mul_f32_e32 v17, 0x4b800000, v16
	s_nop 1
	v_cndmask_b32_e32 v16, v16, v17, vcc
	v_rsq_f32_e32 v16, v16
	s_nop 0
	v_mul_f32_e32 v17, 0x45800000, v16
	v_cndmask_b32_e32 v30, v16, v17, vcc
	s_nop 0
	v_pk_mul_f32 v[14:15], v[30:31], v[14:15] op_sel_hi:[0,1]
	v_pk_mul_f32 v[12:13], v[30:31], v[12:13] op_sel_hi:[0,1]
	v_pk_mul_f32 v[10:11], v[30:31], v[10:11] op_sel_hi:[0,1]
	v_pk_mul_f32 v[8:9], v[30:31], v[8:9] op_sel_hi:[0,1]
	v_pk_mul_f32 v[6:7], v[30:31], v[6:7] op_sel_hi:[0,1]
	v_pk_mul_f32 v[4:5], v[30:31], v[4:5] op_sel_hi:[0,1]
	v_pk_mul_f32 v[2:3], v[30:31], v[2:3] op_sel_hi:[0,1]
	v_pk_mul_f32 v[0:1], v[30:31], v[0:1] op_sel_hi:[0,1]
	s_waitcnt vmcnt(6)
	v_pk_mul_f32 v[12:13], v[132:133], v[12:13]
	v_pk_mul_f32 v[14:15], v[134:135], v[14:15]
	v_pk_add_f32 v[18:19], v[116:117], 1.0 op_sel_hi:[1,0]
	v_pk_add_f32 v[16:17], v[118:119], 1.0 op_sel_hi:[1,0]
	v_pk_fma_f32 v[12:13], v[18:19], v[12:13], v[100:101]
	v_pk_fma_f32 v[14:15], v[16:17], v[14:15], v[102:103]
	v_bfe_u32 v154, v12, 16, 1
	v_add3_u32 v12, v12, v154, s2
	v_bfe_u32 v154, v13, 16, 1
	v_lshrrev_b32_e32 v12, 16, v12
	v_add3_u32 v13, v13, v154, s2
	v_and_or_b32 v12, v13, s18, v12
	v_bfe_u32 v13, v14, 16, 1
	v_add3_u32 v13, v14, v13, s2
	v_bfe_u32 v14, v15, 16, 1
	v_lshrrev_b32_e32 v13, 16, v13
	v_add3_u32 v14, v15, v14, s2
	v_and_or_b32 v13, v14, s18, v13
	global_store_dwordx2 v[20:21], v[12:13], off
	s_waitcnt vmcnt(5)
	v_pk_mul_f32 v[8:9], v[136:137], v[8:9]
	v_pk_mul_f32 v[10:11], v[138:139], v[10:11]
	v_pk_add_f32 v[18:19], v[120:121], 1.0 op_sel_hi:[1,0]
	v_pk_add_f32 v[16:17], v[122:123], 1.0 op_sel_hi:[1,0]
	v_pk_fma_f32 v[8:9], v[18:19], v[8:9], v[104:105]
	v_pk_fma_f32 v[10:11], v[16:17], v[10:11], v[106:107]
	v_bfe_u32 v154, v8, 16, 1
	v_add3_u32 v8, v8, v154, s2
	v_bfe_u32 v154, v9, 16, 1
	v_lshrrev_b32_e32 v8, 16, v8
	v_add3_u32 v9, v9, v154, s2
	v_and_or_b32 v8, v9, s18, v8
	v_bfe_u32 v9, v10, 16, 1
	v_add3_u32 v9, v10, v9, s2
	v_bfe_u32 v10, v11, 16, 1
	v_lshrrev_b32_e32 v9, 16, v9
	v_add3_u32 v10, v11, v10, s2
	v_and_or_b32 v9, v10, s18, v9
	global_store_dwordx2 v[20:21], v[8:9], off offset:512
	s_waitcnt vmcnt(4)
	v_pk_mul_f32 v[4:5], v[140:141], v[4:5]
	v_pk_mul_f32 v[6:7], v[142:143], v[6:7]
	v_pk_add_f32 v[18:19], v[124:125], 1.0 op_sel_hi:[1,0]
	v_pk_add_f32 v[16:17], v[126:127], 1.0 op_sel_hi:[1,0]
	v_pk_fma_f32 v[4:5], v[18:19], v[4:5], v[108:109]
	v_pk_fma_f32 v[6:7], v[16:17], v[6:7], v[110:111]
	v_bfe_u32 v154, v4, 16, 1
	v_add3_u32 v4, v4, v154, s2
	v_bfe_u32 v154, v5, 16, 1
	v_lshrrev_b32_e32 v4, 16, v4
	v_add3_u32 v5, v5, v154, s2
	v_and_or_b32 v4, v5, s18, v4
	v_bfe_u32 v5, v6, 16, 1
	v_add3_u32 v5, v6, v5, s2
	v_bfe_u32 v6, v7, 16, 1
	v_lshrrev_b32_e32 v5, 16, v5
	v_add3_u32 v6, v7, v6, s2
	v_and_or_b32 v5, v6, s18, v5
	global_store_dwordx2 v[20:21], v[4:5], off offset:1024
	s_waitcnt vmcnt(3)
	v_pk_mul_f32 v[0:1], v[144:145], v[0:1]
	v_pk_mul_f32 v[2:3], v[146:147], v[2:3]
	v_pk_add_f32 v[18:19], v[128:129], 1.0 op_sel_hi:[1,0]
	v_pk_add_f32 v[16:17], v[130:131], 1.0 op_sel_hi:[1,0]
	v_pk_fma_f32 v[0:1], v[18:19], v[0:1], v[112:113]
	v_pk_fma_f32 v[2:3], v[16:17], v[2:3], v[114:115]
	v_bfe_u32 v154, v0, 16, 1
	v_add3_u32 v0, v0, v154, s2
	v_bfe_u32 v154, v1, 16, 1
	v_lshrrev_b32_e32 v0, 16, v0
	v_add3_u32 v1, v1, v154, s2
	v_and_or_b32 v0, v1, s18, v0
	v_bfe_u32 v1, v2, 16, 1
	v_add3_u32 v1, v2, v1, s2
	v_bfe_u32 v2, v3, 16, 1
	v_lshrrev_b32_e32 v1, 16, v1
	v_add3_u32 v2, v3, v2, s2
	v_and_or_b32 v1, v2, s18, v1
	global_store_dwordx2 v[20:21], v[0:1], off offset:1536
	v_lshl_add_u64 v[20:21], v[20:21], 0, s[22:23]
	s_add_i32 s4, s4, s72
	s_cmpk_lt_i32 s4, 0x4000
	s_cbranch_scc1 .LBB0_831
